# snake16a MFMA order + raised static priority moved to waves 0-3 + nt on the P0 f32 weight loads
# speedup vs baseline: 1.0042x; 1.0016x over previous
.LBB0_22:
	s_cmpk_gt_u32 s18, 0x7bff
	s_cbranch_scc0 .LBB0_28
	s_cmp_gt_u32 s18, 0x127ff
	s_cbranch_scc0 .LBB0_25
	s_add_i32 s12, s18, 0xfffed800
	s_lshr_b32 s12, s12, 1
	s_and_b32 s13, s12, 0x7fffffc0
	s_and_b32 s12, s1, 0xfe0
	v_or_b32_e32 v2, s12, v47
	v_or_b32_e32 v32, s13, v48
	v_lshlrev_b32_e32 v2, 2, v2
	v_lshl_add_u64 v[34:35], s[46:47], 0, v[2:3]
	v_or_b32_e32 v2, 8, v32
	v_lshlrev_b64 v[6:7], 14, v[2:3]
	v_or_b32_e32 v2, 16, v32
	v_lshlrev_b64 v[12:13], 14, v[2:3]
	v_or_b32_e32 v2, 24, v32
	v_lshlrev_b64 v[14:15], 14, v[2:3]
	v_or_b32_e32 v2, 32, v32
	v_mov_b32_e32 v33, v3
	v_lshlrev_b64 v[20:21], 14, v[2:3]
	v_or_b32_e32 v2, 40, v32
	v_lshlrev_b64 v[4:5], 14, v[32:33]
	v_lshlrev_b64 v[22:23], 14, v[2:3]
	v_lshl_add_u64 v[4:5], v[34:35], 0, v[4:5]
	v_lshl_add_u64 v[8:9], v[34:35], 0, v[6:7]
	v_lshl_add_u64 v[12:13], v[34:35], 0, v[12:13]
	v_lshl_add_u64 v[16:17], v[34:35], 0, v[14:15]
	v_lshl_add_u64 v[20:21], v[34:35], 0, v[20:21]
	v_lshl_add_u64 v[24:25], v[34:35], 0, v[22:23]
	global_load_dwordx4 v[4:7], v[4:5], off nt
	s_nop 0
	global_load_dwordx4 v[8:11], v[8:9], off nt
	s_nop 0
	global_load_dwordx4 v[12:15], v[12:13], off nt
	s_nop 0
	global_load_dwordx4 v[16:19], v[16:17], off nt
	s_nop 0
	global_load_dwordx4 v[20:23], v[20:21], off nt
	s_nop 0
	global_load_dwordx4 v[24:27], v[24:25], off nt
	v_or_b32_e32 v2, 48, v32
	v_lshlrev_b64 v[28:29], 14, v[2:3]
	v_lshl_add_u64 v[28:29], v[34:35], 0, v[28:29]
	v_or_b32_e32 v2, 56, v32
	global_load_dwordx4 v[28:31], v[28:29], off nt
	v_lshlrev_b64 v[32:33], 14, v[2:3]
	v_lshl_add_u64 v[32:33], v[34:35], 0, v[32:33]
	global_load_dwordx4 v[32:35], v[32:33], off nt
	v_or_b32_e32 v2, s12, v48
	s_lshl_b32 s76, s13, 9
	v_lshl_add_u64 v[44:45], v[36:37], 0, s[76:77]
	v_and_b32_e32 v70, 0xff, v2
	v_and_b32_e32 v2, 0xffffff00, v2
	v_mul_u32_u24_e32 v2, 0x5600, v2
	v_lshl_add_u32 v2, v70, 7, v2
	v_lshl_add_u64 v[68:69], v[44:45], 0, v[2:3]
	s_waitcnt vmcnt(7)
	ds_write2_b32 v53, v4, v5 offset1:1
	ds_write2_b32 v53, v6, v7 offset0:2 offset1:3
	s_waitcnt vmcnt(6)
	ds_write2_b32 v54, v8, v9 offset1:1
	ds_write2_b32 v55, v10, v11 offset1:1
	s_waitcnt vmcnt(5)
	ds_write2_b32 v56, v12, v13 offset1:1
	ds_write2_b32 v57, v14, v15 offset1:1
	s_waitcnt vmcnt(4)
	ds_write2_b32 v58, v16, v17 offset1:1
	ds_write2_b32 v59, v18, v19 offset1:1
	s_waitcnt vmcnt(3)
	ds_write2_b32 v60, v20, v21 offset1:1
	ds_write2_b32 v61, v22, v23 offset1:1
	s_waitcnt vmcnt(2)
	ds_write2_b32 v62, v24, v25 offset1:1
	ds_write2_b32 v63, v26, v27 offset1:1
	s_waitcnt vmcnt(1)
	ds_write2_b32 v64, v28, v29 offset1:1
	ds_write2_b32 v65, v30, v31 offset1:1
	s_waitcnt vmcnt(0)
	ds_write2_b32 v66, v32, v33 offset1:1
	ds_write2_b32 v67, v34, v35 offset1:1
	s_waitcnt lgkmcnt(0)
	ds_read2_b32 v[4:5], v52 offset0:33 offset1:41
	ds_read2_b32 v[6:7], v52 offset1:8
	ds_read2_b32 v[8:9], v52 offset0:66 offset1:74
	ds_read2_b32 v[10:11], v52 offset0:99 offset1:107
	ds_read2_b32 v[12:13], v52 offset0:132 offset1:140
	ds_read2_b32 v[14:15], v52 offset0:165 offset1:173
	ds_read2_b32 v[16:17], v52 offset0:198 offset1:206
	ds_read2_b32 v[18:19], v52 offset0:231 offset1:239
	s_waitcnt lgkmcnt(6)
	v_bfe_u32 v2, v6, 16, 1
	v_bfe_u32 v20, v4, 16, 1
	s_waitcnt lgkmcnt(5)
	v_bfe_u32 v21, v8, 16, 1
	s_waitcnt lgkmcnt(4)
	v_bfe_u32 v22, v10, 16, 1
	s_waitcnt lgkmcnt(3)
	v_bfe_u32 v23, v12, 16, 1
	s_waitcnt lgkmcnt(2)
	v_bfe_u32 v24, v14, 16, 1
	s_waitcnt lgkmcnt(1)
	v_bfe_u32 v25, v16, 16, 1
	s_waitcnt lgkmcnt(0)
	v_bfe_u32 v26, v18, 16, 1
	v_bfe_u32 v28, v5, 16, 1
	v_bfe_u32 v29, v9, 16, 1
	v_add3_u32 v2, v6, v2, s20
	v_bfe_u32 v27, v7, 16, 1
	v_bfe_u32 v30, v11, 16, 1
	v_add3_u32 v4, v4, v20, s20
	v_add3_u32 v6, v8, v21, s20
	v_add3_u32 v8, v10, v22, s20
	v_add3_u32 v10, v12, v23, s20
	v_add3_u32 v12, v14, v24, s20
	v_add3_u32 v14, v16, v25, s20
	v_add3_u32 v16, v18, v26, s20
	v_add3_u32 v18, v5, v28, s20
	v_add3_u32 v5, v9, v29, s20
	v_lshrrev_b32_e32 v2, 16, v2
	v_add3_u32 v7, v7, v27, s20
	v_lshrrev_b32_e32 v6, 16, v6
	v_lshrrev_b32_e32 v9, 16, v10
	v_lshrrev_b32_e32 v10, 16, v14
	v_lshrrev_b32_e32 v20, 16, v5
	v_and_or_b32 v4, v4, s21, v2
	v_add3_u32 v2, v11, v30, s20
	v_lshrrev_b32_e32 v14, 16, v7
	v_and_or_b32 v5, v8, s21, v6
	v_and_or_b32 v6, v12, s21, v9
	v_and_or_b32 v7, v16, s21, v10
	v_and_or_b32 v9, v2, s21, v20
	v_bfe_u32 v2, v13, 16, 1
	global_store_dwordx4 v[68:69], v[4:7], off
	v_add3_u32 v2, v13, v2, s20
	v_lshrrev_b32_e32 v2, 16, v2
	v_bfe_u32 v4, v15, 16, 1
	v_add3_u32 v4, v15, v4, s20
	v_and_or_b32 v10, v4, s21, v2
	v_bfe_u32 v2, v17, 16, 1
	v_add3_u32 v2, v17, v2, s20
	v_bfe_u32 v4, v19, 16, 1
	v_lshrrev_b32_e32 v2, 16, v2
	v_add3_u32 v4, v19, v4, s20
	v_and_or_b32 v11, v4, s21, v2
	v_or_b32_e32 v2, s12, v49
	v_and_b32_e32 v70, 0xff, v2
	v_and_b32_e32 v2, 0xffffff00, v2
	v_mul_u32_u24_e32 v2, 0x5600, v2
	v_lshl_add_u32 v2, v70, 7, v2
	v_and_or_b32 v8, v18, s21, v14
	ds_read2_b32 v[12:13], v52 offset0:16 offset1:24
	v_lshl_add_u64 v[4:5], v[44:45], 0, v[2:3]
	global_store_dwordx4 v[4:5], v[8:11], off
	ds_read2_b32 v[8:9], v52 offset0:49 offset1:57
	ds_read2_b32 v[10:11], v52 offset0:82 offset1:90
	ds_read2_b32 v[14:15], v52 offset0:115 offset1:123
	s_waitcnt lgkmcnt(3)
	v_bfe_u32 v2, v12, 16, 1
	v_add3_u32 v2, v12, v2, s20
	s_waitcnt lgkmcnt(2)
	v_bfe_u32 v4, v8, 16, 1
	ds_read2_b32 v[16:17], v52 offset0:148 offset1:156
	v_lshrrev_b32_e32 v2, 16, v2
	v_add3_u32 v4, v8, v4, s20
	ds_read2_b32 v[18:19], v52 offset0:181 offset1:189
	v_and_or_b32 v4, v4, s21, v2
	s_waitcnt lgkmcnt(3)
	v_bfe_u32 v2, v10, 16, 1
	v_add3_u32 v2, v10, v2, s20
	s_waitcnt lgkmcnt(2)
	v_bfe_u32 v5, v14, 16, 1
	ds_read2_b32 v[20:21], v52 offset0:214 offset1:222
	v_lshrrev_b32_e32 v2, 16, v2
	v_add3_u32 v5, v14, v5, s20
	ds_read2_b32 v[22:23], v52 offset0:247 offset1:255
	v_and_or_b32 v5, v5, s21, v2
	s_waitcnt lgkmcnt(3)
	v_bfe_u32 v2, v16, 16, 1
	v_add3_u32 v2, v16, v2, s20
	s_waitcnt lgkmcnt(2)
	v_bfe_u32 v6, v18, 16, 1
	v_lshrrev_b32_e32 v2, 16, v2
	v_add3_u32 v6, v18, v6, s20
	v_and_or_b32 v6, v6, s21, v2
	s_waitcnt lgkmcnt(1)
	v_bfe_u32 v2, v20, 16, 1
	v_add3_u32 v2, v20, v2, s20
	s_waitcnt lgkmcnt(0)
	v_bfe_u32 v7, v22, 16, 1
	v_lshrrev_b32_e32 v2, 16, v2
	v_add3_u32 v7, v22, v7, s20
	v_and_or_b32 v7, v7, s21, v2
	v_or_b32_e32 v2, s12, v50
	v_and_b32_e32 v70, 0xff, v2
	v_and_b32_e32 v2, 0xffffff00, v2
	v_mul_u32_u24_e32 v2, 0x5600, v2
	v_lshl_add_u32 v2, v70, 7, v2
	v_lshl_add_u64 v[24:25], v[44:45], 0, v[2:3]
	v_bfe_u32 v2, v13, 16, 1
	global_store_dwordx4 v[24:25], v[4:7], off
	v_add3_u32 v2, v13, v2, s20
	v_lshrrev_b32_e32 v2, 16, v2
	v_bfe_u32 v4, v9, 16, 1
	v_add3_u32 v4, v9, v4, s20
	v_and_or_b32 v4, v4, s21, v2
	v_bfe_u32 v2, v11, 16, 1
	v_add3_u32 v2, v11, v2, s20
	v_bfe_u32 v5, v15, 16, 1
	v_lshrrev_b32_e32 v2, 16, v2
	v_add3_u32 v5, v15, v5, s20
	v_and_or_b32 v5, v5, s21, v2
	v_bfe_u32 v2, v17, 16, 1
	v_add3_u32 v2, v17, v2, s20
	v_bfe_u32 v6, v19, 16, 1
	v_lshrrev_b32_e32 v2, 16, v2
	v_add3_u32 v6, v19, v6, s20
	v_and_or_b32 v6, v6, s21, v2
	v_bfe_u32 v2, v21, 16, 1
	v_add3_u32 v2, v21, v2, s20
	v_bfe_u32 v7, v23, 16, 1
	v_lshrrev_b32_e32 v2, 16, v2
	v_add3_u32 v7, v23, v7, s20
	v_and_or_b32 v7, v7, s21, v2
	v_or_b32_e32 v2, s12, v51
	v_and_b32_e32 v70, 0xff, v2
	v_and_b32_e32 v2, 0xffffff00, v2
	v_mul_u32_u24_e32 v2, 0x5600, v2
	v_lshl_add_u32 v2, v70, 7, v2
	v_lshl_add_u64 v[8:9], v[44:45], 0, v[2:3]
	global_store_dwordx4 v[8:9], v[4:7], off
	s_waitcnt lgkmcnt(0)
	s_mov_b64 s[12:13], 0
.LBB0_25:
	s_andn2_b64 vcc, exec, s[12:13]
	s_cbranch_vccnz .LBB0_27
	s_add_i32 s12, s18, 0x8400
	s_and_b32 s13, s12, 0xffff
	s_mul_i32 s13, s13, 0xbe83
	s_lshr_b32 s13, s13, 25
	s_mul_i32 s14, s13, 0x2b0
	s_sub_i32 s12, s12, s14
	s_and_b32 s19, s12, 0xffff
	s_bitcmp0_b32 s12, 2
	s_cselect_b32 s14, s48, s50
	s_cselect_b32 s12, s49, s51
	s_add_u32 s14, s14, s0
	s_addc_u32 s15, s12, 0
	s_lshl_b32 s12, s19, 5
	s_lshl_b32 s19, s19, 4
	s_and_b32 s19, s19, 0x3f80
	s_and_b32 s23, s12, 0x60
	s_or_b32 s19, s19, s23
	v_or_b32_e32 v2, s19, v47
	v_lshl_or_b32 v6, s13, 6, v48
	v_lshlrev_b32_e32 v2, 2, v2
	v_lshl_add_u64 v[4:5], s[14:15], 0, v[2:3]
	v_mul_u32_u24_e32 v2, 0xac00, v6
	v_lshl_add_u64 v[32:33], v[4:5], 0, v[2:3]
	s_mov_b32 s14, 0x56000
	v_add_co_u32_e32 v8, vcc, s14, v32
	s_mov_b32 s14, 0xac000
	s_nop 0
	v_addc_co_u32_e32 v9, vcc, 0, v33, vcc
	v_add_co_u32_e32 v12, vcc, s14, v32
	s_mov_b32 s14, 0x102000
	s_nop 0
	v_addc_co_u32_e32 v13, vcc, 0, v33, vcc
	v_add_co_u32_e32 v16, vcc, s14, v32
	s_mov_b32 s14, 0x158000
	s_nop 0
	v_addc_co_u32_e32 v17, vcc, 0, v33, vcc
	v_add_co_u32_e32 v20, vcc, s14, v32
	s_mov_b32 s14, 0x1ae000
	s_nop 0
	v_addc_co_u32_e32 v21, vcc, 0, v33, vcc
	v_add_co_u32_e32 v24, vcc, s14, v32
	global_load_dwordx4 v[4:7], v[32:33], off nt
	s_nop 0
	global_load_dwordx4 v[8:11], v[8:9], off nt
	v_addc_co_u32_e32 v25, vcc, 0, v33, vcc
	global_load_dwordx4 v[12:15], v[12:13], off nt
	s_nop 0
	global_load_dwordx4 v[16:19], v[16:17], off nt
	s_nop 0
	global_load_dwordx4 v[20:23], v[20:21], off nt
	s_nop 0
	global_load_dwordx4 v[24:27], v[24:25], off nt
	s_mov_b32 s14, 0x204000
	v_add_co_u32_e32 v28, vcc, s14, v32
	s_mov_b32 s14, 0x25a000
	s_nop 0
	v_addc_co_u32_e32 v29, vcc, 0, v33, vcc
	global_load_dwordx4 v[28:31], v[28:29], off nt
	v_add_co_u32_e32 v32, vcc, s14, v32
	s_lshl_b32 s76, s13, 7
	s_nop 0
	v_addc_co_u32_e32 v33, vcc, 0, v33, vcc
	global_load_dwordx4 v[32:35], v[32:33], off nt
	v_lshl_add_u64 v[44:45], v[38:39], 0, s[76:77]
	s_waitcnt vmcnt(7)
	ds_write2_b32 v53, v4, v5 offset1:1
	ds_write2_b32 v53, v6, v7 offset0:2 offset1:3
	s_waitcnt vmcnt(6)
	ds_write2_b32 v54, v8, v9 offset1:1
	ds_write2_b32 v55, v10, v11 offset1:1
	s_waitcnt vmcnt(5)
	ds_write2_b32 v56, v12, v13 offset1:1
	ds_write2_b32 v57, v14, v15 offset1:1
	s_waitcnt vmcnt(4)
	ds_write2_b32 v58, v16, v17 offset1:1
	ds_write2_b32 v59, v18, v19 offset1:1
	s_waitcnt vmcnt(3)
	ds_write2_b32 v60, v20, v21 offset1:1
	ds_write2_b32 v61, v22, v23 offset1:1
	s_waitcnt vmcnt(2)
	ds_write2_b32 v62, v24, v25 offset1:1
	ds_write2_b32 v63, v26, v27 offset1:1
	s_waitcnt vmcnt(1)
	ds_write2_b32 v64, v28, v29 offset1:1
	ds_write2_b32 v65, v30, v31 offset1:1
	s_waitcnt vmcnt(0)
	ds_write2_b32 v66, v32, v33 offset1:1
	ds_write2_b32 v67, v34, v35 offset1:1
	s_waitcnt lgkmcnt(0)
	ds_read2_b32 v[8:9], v52 offset0:33 offset1:41
	ds_read2_b32 v[10:11], v52 offset1:8
	ds_read2_b32 v[12:13], v52 offset0:66 offset1:74
	ds_read2_b32 v[14:15], v52 offset0:99 offset1:107
	ds_read2_b32 v[16:17], v52 offset0:132 offset1:140
	ds_read2_b32 v[18:19], v52 offset0:165 offset1:173
	ds_read2_b32 v[20:21], v52 offset0:198 offset1:206
	ds_read2_b32 v[22:23], v52 offset0:231 offset1:239
	s_waitcnt lgkmcnt(6)
	v_bfe_u32 v2, v10, 16, 1
	v_bfe_u32 v4, v8, 16, 1
	v_add3_u32 v2, v10, v2, s20
	s_waitcnt lgkmcnt(5)
	v_bfe_u32 v5, v12, 16, 1
	s_waitcnt lgkmcnt(3)
	v_bfe_u32 v7, v16, 16, 1
	s_waitcnt lgkmcnt(1)
	v_bfe_u32 v25, v20, 16, 1
	v_add3_u32 v4, v8, v4, s20
	v_lshrrev_b32_e32 v2, 16, v2
	v_bfe_u32 v6, v14, 16, 1
	v_bfe_u32 v24, v18, 16, 1
	s_waitcnt lgkmcnt(0)
	v_bfe_u32 v26, v22, 16, 1
	v_add3_u32 v5, v12, v5, s20
	v_add3_u32 v7, v16, v7, s20
	v_add3_u32 v10, v20, v25, s20
	v_and_or_b32 v4, v4, s21, v2
	v_or_b32_e32 v2, s12, v48
	v_add3_u32 v6, v14, v6, s20
	v_add3_u32 v8, v18, v24, s20
	v_add3_u32 v12, v22, v26, s20
	v_lshrrev_b32_e32 v5, 16, v5
	v_lshrrev_b32_e32 v7, 16, v7
	v_lshrrev_b32_e32 v10, 16, v10
	v_lshlrev_b32_e32 v2, 13, v2
	v_and_or_b32 v5, v6, s21, v5
	v_and_or_b32 v6, v8, s21, v7
	v_and_or_b32 v7, v12, s21, v10
	v_lshl_add_u64 v[24:25], v[44:45], 0, v[2:3]
	v_bfe_u32 v2, v11, 16, 1
	global_store_dwordx4 v[24:25], v[4:7], off
	v_add3_u32 v2, v11, v2, s20
	v_lshrrev_b32_e32 v2, 16, v2
	v_bfe_u32 v4, v9, 16, 1
	v_add3_u32 v4, v9, v4, s20
	v_and_or_b32 v4, v4, s21, v2
	v_bfe_u32 v2, v13, 16, 1
	v_add3_u32 v2, v13, v2, s20
	v_bfe_u32 v5, v15, 16, 1
	v_lshrrev_b32_e32 v2, 16, v2
	v_add3_u32 v5, v15, v5, s20
	v_and_or_b32 v5, v5, s21, v2
	v_bfe_u32 v2, v17, 16, 1
	v_add3_u32 v2, v17, v2, s20
	v_bfe_u32 v6, v19, 16, 1
	v_lshrrev_b32_e32 v2, 16, v2
	v_add3_u32 v6, v19, v6, s20
	v_and_or_b32 v6, v6, s21, v2
	v_bfe_u32 v2, v21, 16, 1
	v_add3_u32 v2, v21, v2, s20
	v_bfe_u32 v7, v23, 16, 1
	v_lshrrev_b32_e32 v2, 16, v2
	v_add3_u32 v7, v23, v7, s20
	v_and_or_b32 v7, v7, s21, v2
	v_or_b32_e32 v2, s12, v49
	v_lshlrev_b32_e32 v2, 13, v2
	ds_read2_b32 v[8:9], v52 offset0:16 offset1:24
	v_lshl_add_u64 v[10:11], v[44:45], 0, v[2:3]
	global_store_dwordx4 v[10:11], v[4:7], off
	ds_read2_b32 v[10:11], v52 offset0:49 offset1:57
	ds_read2_b32 v[12:13], v52 offset0:82 offset1:90
	ds_read2_b32 v[14:15], v52 offset0:115 offset1:123
	s_waitcnt lgkmcnt(3)
	v_bfe_u32 v2, v8, 16, 1
	v_add3_u32 v2, v8, v2, s20
	s_waitcnt lgkmcnt(2)
	v_bfe_u32 v4, v10, 16, 1
	ds_read2_b32 v[16:17], v52 offset0:148 offset1:156
	v_lshrrev_b32_e32 v2, 16, v2
	v_add3_u32 v4, v10, v4, s20
	ds_read2_b32 v[18:19], v52 offset0:181 offset1:189
	v_and_or_b32 v4, v4, s21, v2
	s_waitcnt lgkmcnt(3)
	v_bfe_u32 v2, v12, 16, 1
	v_add3_u32 v2, v12, v2, s20
	s_waitcnt lgkmcnt(2)
	v_bfe_u32 v5, v14, 16, 1
	ds_read2_b32 v[20:21], v52 offset0:214 offset1:222
	v_lshrrev_b32_e32 v2, 16, v2
	v_add3_u32 v5, v14, v5, s20
	ds_read2_b32 v[22:23], v52 offset0:247 offset1:255
	v_and_or_b32 v5, v5, s21, v2
	s_waitcnt lgkmcnt(3)
	v_bfe_u32 v2, v16, 16, 1
	v_add3_u32 v2, v16, v2, s20
	s_waitcnt lgkmcnt(2)
	v_bfe_u32 v6, v18, 16, 1
	v_lshrrev_b32_e32 v2, 16, v2
	v_add3_u32 v6, v18, v6, s20
	v_and_or_b32 v6, v6, s21, v2
	s_waitcnt lgkmcnt(1)
	v_bfe_u32 v2, v20, 16, 1
	v_add3_u32 v2, v20, v2, s20
	s_waitcnt lgkmcnt(0)
	v_bfe_u32 v7, v22, 16, 1
	v_lshrrev_b32_e32 v2, 16, v2
	v_add3_u32 v7, v22, v7, s20
	v_and_or_b32 v7, v7, s21, v2
	v_or_b32_e32 v2, s12, v50
	v_lshlrev_b32_e32 v2, 13, v2
	v_lshl_add_u64 v[24:25], v[44:45], 0, v[2:3]
	v_bfe_u32 v2, v9, 16, 1
	global_store_dwordx4 v[24:25], v[4:7], off
	v_add3_u32 v2, v9, v2, s20
	v_lshrrev_b32_e32 v2, 16, v2
	v_bfe_u32 v4, v11, 16, 1
	v_add3_u32 v4, v11, v4, s20
	v_and_or_b32 v4, v4, s21, v2
	v_bfe_u32 v2, v13, 16, 1
	v_add3_u32 v2, v13, v2, s20
	v_bfe_u32 v5, v15, 16, 1
	v_lshrrev_b32_e32 v2, 16, v2
	v_add3_u32 v5, v15, v5, s20
	v_and_or_b32 v5, v5, s21, v2
	v_bfe_u32 v2, v17, 16, 1
	v_add3_u32 v2, v17, v2, s20
	v_bfe_u32 v6, v19, 16, 1
	v_lshrrev_b32_e32 v2, 16, v2
	v_add3_u32 v6, v19, v6, s20
	v_and_or_b32 v6, v6, s21, v2
	v_bfe_u32 v2, v21, 16, 1
	v_add3_u32 v2, v21, v2, s20
	v_bfe_u32 v7, v23, 16, 1
	v_lshrrev_b32_e32 v2, 16, v2
	v_add3_u32 v7, v23, v7, s20
	v_and_or_b32 v7, v7, s21, v2
	v_or_b32_e32 v2, s12, v51
	v_lshlrev_b32_e32 v2, 13, v2
	v_lshl_add_u64 v[8:9], v[44:45], 0, v[2:3]
	global_store_dwordx4 v[8:9], v[4:7], off
	s_waitcnt lgkmcnt(0)

.LBB0_28:
	s_andn2_b64 vcc, exec, s[12:13]
	s_cbranch_vccnz .LBB0_30
	s_add_i32 s12, s18, 0xffffa400
	s_lshr_b32 s12, s12, 1
	s_and_b32 s13, s12, 0x7fffffc0
	s_and_b32 s12, s1, 0xfe0
	v_or_b32_e32 v2, s12, v47
	v_or_b32_e32 v32, s13, v48
	v_lshlrev_b32_e32 v2, 2, v2
	v_lshl_add_u64 v[34:35], s[42:43], 0, v[2:3]
	v_or_b32_e32 v2, 8, v32
	v_lshlrev_b64 v[6:7], 14, v[2:3]
	v_or_b32_e32 v2, 16, v32
	v_lshlrev_b64 v[12:13], 14, v[2:3]
	v_or_b32_e32 v2, 24, v32
	v_lshlrev_b64 v[14:15], 14, v[2:3]
	v_or_b32_e32 v2, 32, v32
	v_mov_b32_e32 v33, v3
	v_lshlrev_b64 v[20:21], 14, v[2:3]
	v_or_b32_e32 v2, 40, v32
	v_lshlrev_b64 v[4:5], 14, v[32:33]
	v_lshlrev_b64 v[22:23], 14, v[2:3]
	v_lshl_add_u64 v[4:5], v[34:35], 0, v[4:5]
	v_lshl_add_u64 v[8:9], v[34:35], 0, v[6:7]
	v_lshl_add_u64 v[12:13], v[34:35], 0, v[12:13]
	v_lshl_add_u64 v[16:17], v[34:35], 0, v[14:15]
	v_lshl_add_u64 v[20:21], v[34:35], 0, v[20:21]
	v_lshl_add_u64 v[24:25], v[34:35], 0, v[22:23]
	global_load_dwordx4 v[4:7], v[4:5], off nt
	s_nop 0
	global_load_dwordx4 v[8:11], v[8:9], off nt
	s_nop 0
	global_load_dwordx4 v[12:15], v[12:13], off nt
	s_nop 0
	global_load_dwordx4 v[16:19], v[16:17], off nt
	s_nop 0
	global_load_dwordx4 v[20:23], v[20:21], off nt
	s_nop 0
	global_load_dwordx4 v[24:27], v[24:25], off nt
	v_or_b32_e32 v2, 48, v32
	v_lshlrev_b64 v[28:29], 14, v[2:3]
	v_lshl_add_u64 v[28:29], v[34:35], 0, v[28:29]
	v_or_b32_e32 v2, 56, v32
	global_load_dwordx4 v[28:31], v[28:29], off nt
	v_lshlrev_b64 v[32:33], 14, v[2:3]
	v_lshl_add_u64 v[32:33], v[34:35], 0, v[32:33]
	global_load_dwordx4 v[32:35], v[32:33], off nt
	v_or_b32_e32 v2, s12, v48
	s_lshl_b32 s76, s13, 1
	v_lshl_add_u64 v[44:45], v[40:41], 0, s[76:77]
	v_lshlrev_b32_e32 v2, 13, v2
	v_lshl_add_u64 v[68:69], v[44:45], 0, v[2:3]
	s_waitcnt vmcnt(7)
	ds_write2_b32 v53, v4, v5 offset1:1
	ds_write2_b32 v53, v6, v7 offset0:2 offset1:3
	s_waitcnt vmcnt(6)
	ds_write2_b32 v54, v8, v9 offset1:1
	ds_write2_b32 v55, v10, v11 offset1:1
	s_waitcnt vmcnt(5)
	ds_write2_b32 v56, v12, v13 offset1:1
	ds_write2_b32 v57, v14, v15 offset1:1
	s_waitcnt vmcnt(4)
	ds_write2_b32 v58, v16, v17 offset1:1
	ds_write2_b32 v59, v18, v19 offset1:1
	s_waitcnt vmcnt(3)
	ds_write2_b32 v60, v20, v21 offset1:1
	ds_write2_b32 v61, v22, v23 offset1:1
	s_waitcnt vmcnt(2)
	ds_write2_b32 v62, v24, v25 offset1:1
	ds_write2_b32 v63, v26, v27 offset1:1
	s_waitcnt vmcnt(1)
	ds_write2_b32 v64, v28, v29 offset1:1
	ds_write2_b32 v65, v30, v31 offset1:1
	s_waitcnt vmcnt(0)
	ds_write2_b32 v66, v32, v33 offset1:1
	ds_write2_b32 v67, v34, v35 offset1:1
	s_waitcnt lgkmcnt(0)
	ds_read2_b32 v[4:5], v52 offset0:33 offset1:41
	ds_read2_b32 v[6:7], v52 offset1:8
	ds_read2_b32 v[8:9], v52 offset0:66 offset1:74
	ds_read2_b32 v[10:11], v52 offset0:99 offset1:107
	ds_read2_b32 v[12:13], v52 offset0:132 offset1:140
	ds_read2_b32 v[14:15], v52 offset0:165 offset1:173
	ds_read2_b32 v[16:17], v52 offset0:198 offset1:206
	ds_read2_b32 v[18:19], v52 offset0:231 offset1:239
	s_waitcnt lgkmcnt(6)
	v_bfe_u32 v2, v6, 16, 1
	v_bfe_u32 v20, v4, 16, 1
	s_waitcnt lgkmcnt(5)
	v_bfe_u32 v21, v8, 16, 1
	s_waitcnt lgkmcnt(4)
	v_bfe_u32 v22, v10, 16, 1
	s_waitcnt lgkmcnt(3)
	v_bfe_u32 v23, v12, 16, 1
	s_waitcnt lgkmcnt(2)
	v_bfe_u32 v24, v14, 16, 1
	s_waitcnt lgkmcnt(1)
	v_bfe_u32 v25, v16, 16, 1
	s_waitcnt lgkmcnt(0)
	v_bfe_u32 v26, v18, 16, 1
	v_bfe_u32 v28, v5, 16, 1
	v_bfe_u32 v29, v9, 16, 1
	v_add3_u32 v2, v6, v2, s20
	v_bfe_u32 v27, v7, 16, 1
	v_bfe_u32 v30, v11, 16, 1
	v_add3_u32 v4, v4, v20, s20
	v_add3_u32 v6, v8, v21, s20
	v_add3_u32 v8, v10, v22, s20
	v_add3_u32 v10, v12, v23, s20
	v_add3_u32 v12, v14, v24, s20
	v_add3_u32 v14, v16, v25, s20
	v_add3_u32 v16, v18, v26, s20
	v_add3_u32 v18, v5, v28, s20
	v_add3_u32 v5, v9, v29, s20
	v_lshrrev_b32_e32 v2, 16, v2
	v_add3_u32 v7, v7, v27, s20
	v_lshrrev_b32_e32 v6, 16, v6
	v_lshrrev_b32_e32 v9, 16, v10
	v_lshrrev_b32_e32 v10, 16, v14
	v_lshrrev_b32_e32 v20, 16, v5
	v_and_or_b32 v4, v4, s21, v2
	v_add3_u32 v2, v11, v30, s20
	v_lshrrev_b32_e32 v14, 16, v7
	v_and_or_b32 v5, v8, s21, v6
	v_and_or_b32 v6, v12, s21, v9
	v_and_or_b32 v7, v16, s21, v10
	v_and_or_b32 v9, v2, s21, v20
	v_bfe_u32 v2, v13, 16, 1
	global_store_dwordx4 v[68:69], v[4:7], off
	v_add3_u32 v2, v13, v2, s20
	v_lshrrev_b32_e32 v2, 16, v2
	v_bfe_u32 v4, v15, 16, 1
	v_add3_u32 v4, v15, v4, s20
	v_and_or_b32 v10, v4, s21, v2
	v_bfe_u32 v2, v17, 16, 1
	v_add3_u32 v2, v17, v2, s20
	v_bfe_u32 v4, v19, 16, 1
	v_lshrrev_b32_e32 v2, 16, v2
	v_add3_u32 v4, v19, v4, s20
	v_and_or_b32 v11, v4, s21, v2
	v_or_b32_e32 v2, s12, v49
	v_lshlrev_b32_e32 v2, 13, v2
	v_and_or_b32 v8, v18, s21, v14
	ds_read2_b32 v[12:13], v52 offset0:16 offset1:24
	v_lshl_add_u64 v[4:5], v[44:45], 0, v[2:3]
	global_store_dwordx4 v[4:5], v[8:11], off
	ds_read2_b32 v[8:9], v52 offset0:49 offset1:57
	ds_read2_b32 v[10:11], v52 offset0:82 offset1:90
	ds_read2_b32 v[14:15], v52 offset0:115 offset1:123
	s_waitcnt lgkmcnt(3)
	v_bfe_u32 v2, v12, 16, 1
	v_add3_u32 v2, v12, v2, s20
	s_waitcnt lgkmcnt(2)
	v_bfe_u32 v4, v8, 16, 1
	ds_read2_b32 v[16:17], v52 offset0:148 offset1:156
	v_lshrrev_b32_e32 v2, 16, v2
	v_add3_u32 v4, v8, v4, s20
	ds_read2_b32 v[18:19], v52 offset0:181 offset1:189
	v_and_or_b32 v4, v4, s21, v2
	s_waitcnt lgkmcnt(3)
	v_bfe_u32 v2, v10, 16, 1
	v_add3_u32 v2, v10, v2, s20
	s_waitcnt lgkmcnt(2)
	v_bfe_u32 v5, v14, 16, 1
	ds_read2_b32 v[20:21], v52 offset0:214 offset1:222
	v_lshrrev_b32_e32 v2, 16, v2
	v_add3_u32 v5, v14, v5, s20
	ds_read2_b32 v[22:23], v52 offset0:247 offset1:255
	v_and_or_b32 v5, v5, s21, v2
	s_waitcnt lgkmcnt(3)
	v_bfe_u32 v2, v16, 16, 1
	v_add3_u32 v2, v16, v2, s20
	s_waitcnt lgkmcnt(2)
	v_bfe_u32 v6, v18, 16, 1
	v_lshrrev_b32_e32 v2, 16, v2
	v_add3_u32 v6, v18, v6, s20
	v_and_or_b32 v6, v6, s21, v2
	s_waitcnt lgkmcnt(1)
	v_bfe_u32 v2, v20, 16, 1
	v_add3_u32 v2, v20, v2, s20
	s_waitcnt lgkmcnt(0)
	v_bfe_u32 v7, v22, 16, 1
	v_lshrrev_b32_e32 v2, 16, v2
	v_add3_u32 v7, v22, v7, s20
	v_and_or_b32 v7, v7, s21, v2
	v_or_b32_e32 v2, s12, v50
	v_lshlrev_b32_e32 v2, 13, v2
	v_lshl_add_u64 v[24:25], v[44:45], 0, v[2:3]
	v_bfe_u32 v2, v13, 16, 1
	global_store_dwordx4 v[24:25], v[4:7], off
	v_add3_u32 v2, v13, v2, s20
	v_lshrrev_b32_e32 v2, 16, v2
	v_bfe_u32 v4, v9, 16, 1
	v_add3_u32 v4, v9, v4, s20
	v_and_or_b32 v4, v4, s21, v2
	v_bfe_u32 v2, v11, 16, 1
	v_add3_u32 v2, v11, v2, s20
	v_bfe_u32 v5, v15, 16, 1
	v_lshrrev_b32_e32 v2, 16, v2
	v_add3_u32 v5, v15, v5, s20
	v_and_or_b32 v5, v5, s21, v2
	v_bfe_u32 v2, v17, 16, 1
	v_add3_u32 v2, v17, v2, s20
	v_bfe_u32 v6, v19, 16, 1
	v_lshrrev_b32_e32 v2, 16, v2
	v_add3_u32 v6, v19, v6, s20
	v_and_or_b32 v6, v6, s21, v2
	v_bfe_u32 v2, v21, 16, 1
	v_add3_u32 v2, v21, v2, s20
	v_bfe_u32 v7, v23, 16, 1
	v_lshrrev_b32_e32 v2, 16, v2
	v_add3_u32 v7, v23, v7, s20
	v_and_or_b32 v7, v7, s21, v2
	v_or_b32_e32 v2, s12, v51
	v_lshlrev_b32_e32 v2, 13, v2
	v_lshl_add_u64 v[8:9], v[44:45], 0, v[2:3]
	global_store_dwordx4 v[8:9], v[4:7], off
	s_waitcnt lgkmcnt(0)

.LBB0_36:
	s_or_b64 exec, exec, s[12:13]
	s_lshl_b32 s12, s23, 6
	v_cmp_lt_i32_e32 vcc, -1, v2
	v_or_b32_e32 v68, s12, v48
	v_lshl_add_u64 v[44:45], v[2:3], 2, s[38:39]
	v_mov_b32_e32 v4, 0
	v_mov_b32_e32 v8, 0
	v_mov_b32_e32 v9, 0
	v_mov_b32_e32 v10, 0
	v_mov_b32_e32 v11, 0
	s_and_saveexec_b64 s[14:15], vcc
	s_cbranch_execz .LBB0_38
	s_mov_b32 s13, 0xb440
	v_mad_i64_i32 v[6:7], s[24:25], v68, s13, v[44:45]
	global_load_dwordx4 v[8:11], v[6:7], off nt
.LBB0_38:
	s_or_b64 exec, exec, s[14:15]
	v_mov_b32_e32 v5, 0
	v_mov_b32_e32 v6, 0
	v_mov_b32_e32 v7, 0
	s_and_saveexec_b64 s[14:15], vcc
	s_cbranch_execz .LBB0_40
	v_or_b32_e32 v2, 8, v68
	s_mov_b32 s13, 0xb440
	v_mad_i64_i32 v[4:5], s[24:25], v2, s13, v[44:45]
	global_load_dwordx4 v[4:7], v[4:5], off nt
.LBB0_40:
	s_or_b64 exec, exec, s[14:15]
	v_mov_b32_e32 v12, 0
	v_mov_b32_e32 v16, 0
	v_mov_b32_e32 v17, 0
	v_mov_b32_e32 v18, 0
	v_mov_b32_e32 v19, 0
	s_and_saveexec_b64 s[14:15], vcc
	s_cbranch_execz .LBB0_42
	v_or_b32_e32 v2, 16, v68
	s_mov_b32 s13, 0xb440
	v_mad_i64_i32 v[14:15], s[24:25], v2, s13, v[44:45]
	global_load_dwordx4 v[16:19], v[14:15], off nt
.LBB0_42:
	s_or_b64 exec, exec, s[14:15]
	v_mov_b32_e32 v13, 0
	v_mov_b32_e32 v14, 0
	v_mov_b32_e32 v15, 0
	s_and_saveexec_b64 s[14:15], vcc
	s_cbranch_execz .LBB0_44
	v_or_b32_e32 v2, 24, v68
	s_mov_b32 s13, 0xb440
	v_mad_i64_i32 v[12:13], s[24:25], v2, s13, v[44:45]
	global_load_dwordx4 v[12:15], v[12:13], off nt
.LBB0_44:
	s_or_b64 exec, exec, s[14:15]
	v_mov_b32_e32 v20, 0
	v_mov_b32_e32 v24, 0
	v_mov_b32_e32 v25, 0
	v_mov_b32_e32 v26, 0
	v_mov_b32_e32 v27, 0
	s_and_saveexec_b64 s[14:15], vcc
	s_cbranch_execz .LBB0_46
	v_or_b32_e32 v2, 32, v68
	s_mov_b32 s13, 0xb440
	v_mad_i64_i32 v[22:23], s[24:25], v2, s13, v[44:45]
	global_load_dwordx4 v[24:27], v[22:23], off nt
.LBB0_46:
	s_or_b64 exec, exec, s[14:15]
	v_mov_b32_e32 v21, 0
	v_mov_b32_e32 v22, 0
	v_mov_b32_e32 v23, 0
	s_and_saveexec_b64 s[14:15], vcc
	s_cbranch_execz .LBB0_48
	v_or_b32_e32 v2, 40, v68
	s_mov_b32 s13, 0xb440
	v_mad_i64_i32 v[20:21], s[24:25], v2, s13, v[44:45]
	global_load_dwordx4 v[20:23], v[20:21], off nt
.LBB0_48:
	s_or_b64 exec, exec, s[14:15]
	v_mov_b32_e32 v28, 0
	v_mov_b32_e32 v32, 0
	v_mov_b32_e32 v33, 0
	v_mov_b32_e32 v34, 0
	v_mov_b32_e32 v35, 0
	s_and_saveexec_b64 s[14:15], vcc
	s_cbranch_execz .LBB0_50
	v_or_b32_e32 v2, 48, v68
	s_mov_b32 s13, 0xb440
	v_mad_i64_i32 v[30:31], s[24:25], v2, s13, v[44:45]
	global_load_dwordx4 v[32:35], v[30:31], off nt
.LBB0_50:
	s_or_b64 exec, exec, s[14:15]
	v_mov_b32_e32 v29, 0
	v_mov_b32_e32 v30, 0
	v_mov_b32_e32 v31, 0
	s_and_saveexec_b64 s[14:15], vcc
	s_cbranch_execz .LBB0_18
	v_or_b32_e32 v2, 56, v68
	s_mov_b32 s13, 0xb440
	v_mad_i64_i32 v[28:29], s[24:25], v2, s13, v[44:45]
	global_load_dwordx4 v[28:31], v[28:29], off nt
	s_branch .LBB0_18

.LBB0_117:
	s_cmp_le_i32 s28, s34
	s_cselect_b64 s[0:1], -1, 0
	s_and_b64 s[12:13], s[0:1], s[6:7]
	v_readlane_b32 s0, v255, 2
	s_add_i32 s0, s0, 2
	s_cmp_lt_i32 s0, s29
	s_cselect_b64 s[6:7], -1, 0
	s_andn2_b64 vcc, exec, s[12:13]
	s_cbranch_vccnz .LBB0_188
	v_readlane_b32 s14, v252, 53
	v_mov_b32_e32 v1, v0
	s_mov_b64 s[12:13], s[72:73]
	s_waitcnt vmcnt(1)
	v_mov_b32_e32 v12, v0
	v_readlane_b32 s15, v252, 54
	s_andn2_b64 vcc, exec, s[14:15]
	v_readfirstlane_b32 s35, v12
	s_cbranch_vccnz .LBB0_134
	v_lshlrev_b32_e32 v1, 4, v12
	s_waitcnt lgkmcnt(0)
	v_add_u32_e32 v2, 0x2000, v1
	v_ashrrev_i32_e32 v4, 31, v2
	v_lshrrev_b32_e32 v4, 22, v4
	v_add_u32_e32 v4, v2, v4
	v_ashrrev_i32_e32 v13, 10, v4
	v_mul_i32_i24_e32 v4, 0x400, v13
	v_sub_u32_e32 v2, v2, v4
	v_lshrrev_b32_e32 v4, 4, v2
	v_bitop3_b32 v2, v4, v2, 32 bitop3:0x6c
	v_ashrrev_i32_e32 v4, 31, v2
	v_lshrrev_b32_e32 v4, 26, v4
	v_add_u32_e32 v4, v2, v4
	v_lshlrev_b32_e32 v5, 3, v13
	s_waitcnt vmcnt(0)
	v_ashrrev_i32_e32 v14, 6, v4
	v_and_b32_e32 v5, -16, v5
	v_add_u32_e32 v5, v14, v5
	s_load_dwordx2 s[18:19], s[12:13], 0x98
	v_and_b32_e32 v6, 3, v14
	s_mov_b32 s12, 0x7ffe0
	v_lshrrev_b32_e32 v7, 2, v5
	v_lshlrev_b32_e32 v8, 1, v5
	v_and_or_b32 v6, v5, s12, v6
	v_and_b32_e32 v7, 4, v7
	v_and_b32_e32 v8, 24, v8
	v_and_b32_e32 v4, 0xc0, v4
	v_or3_b32 v6, v6, v7, v8
	v_sub_u32_e32 v2, v2, v4
	v_mov_b32_e32 v8, 1
	v_lshlrev_b32_e32 v7, 5, v13
	v_ashrrev_i16_sdwa v2, v8, sext(v2) dst_sel:DWORD dst_unused:UNUSED_PAD src0_sel:DWORD src1_sel:BYTE_0
	v_and_b32_e32 v7, 32, v7
	v_bfe_i32 v15, v2, 0, 16
	v_add_lshl_u32 v2, v7, v15, 1
	v_lshl_add_u32 v132, v6, 13, v2
	v_lshl_add_u32 v134, v5, 13, v2
	v_bfe_i32 v2, v12, 27, 1
	v_lshrrev_b32_e32 v2, 22, v2
	v_add_u32_e32 v2, v1, v2
	v_and_b32_e32 v2, 0xfffffc00, v2
	v_sub_u32_e32 v1, v1, v2
	v_lshrrev_b32_e32 v2, 4, v1
	v_ashrrev_i32_e32 v4, 31, v12
	v_bitop3_b32 v1, v2, v1, 32 bitop3:0x6c
	v_lshrrev_b32_e32 v4, 26, v4
	v_ashrrev_i32_e32 v2, 31, v1
	v_add_u32_e32 v4, v12, v4
	v_lshrrev_b32_e32 v2, 26, v2
	v_ashrrev_i32_e32 v17, 6, v4
	v_add_u32_e32 v2, v1, v2
	v_lshlrev_b32_e32 v4, 3, v17
	s_waitcnt lgkmcnt(0)
	s_add_u32 s1, s18, 0x18000000
	v_ashrrev_i32_e32 v16, 6, v2
	v_and_b32_e32 v4, -16, v4
	s_addc_u32 s3, s19, 0
	v_add_u32_e32 v4, v16, v4
	s_add_u32 s24, s18, 0x200000
	v_and_b32_e32 v5, 3, v16
	v_lshrrev_b32_e32 v6, 2, v4
	v_lshlrev_b32_e32 v7, 1, v4
	v_and_b32_e32 v2, 0xc0, v2
	s_addc_u32 s25, s19, 0
	s_ashr_i32 s31, s35, 6
	v_and_or_b32 v5, v4, s12, v5
	v_and_b32_e32 v6, 4, v6
	v_and_b32_e32 v7, 24, v7
	v_sub_u32_e32 v1, v1, v2
	s_ashr_i32 s36, s35, 8
	s_cbranch_scc1 .Lsp_p1
	s_setprio 1

.LBB0_999:
	s_cmp_le_i32 s28, s34
	s_cselect_b64 s[0:1], -1, 0
	v_readlane_b32 s3, v255, 2
	s_and_b64 s[0:1], s[0:1], s[6:7]
	s_add_i32 s34, s3, 6
	s_cmp_lt_i32 s34, s29
	s_cselect_b64 s[6:7], -1, 0
	s_andn2_b64 vcc, exec, s[0:1]
	v_readlane_b32 s0, v253, 4
	v_readlane_b32 s1, v253, 5
	s_nop 1
	v_cndmask_b32_e64 v1, 0, 1, s[0:1]
	s_waitcnt lgkmcnt(0)
	v_cmp_ne_u32_e64 s[38:39], 1, v1
	s_cbranch_vccnz .LBB0_1090
	v_mov_b32_e32 v1, v0
	s_mov_b64 s[12:13], s[72:73]
	s_waitcnt vmcnt(1)
	v_mov_b32_e32 v12, v0
	s_and_b64 vcc, exec, s[38:39]
	v_readfirstlane_b32 s0, v12
	s_cbranch_vccnz .LBB0_1036
	v_lshlrev_b32_e32 v1, 4, v12
	v_add_u32_e32 v2, 0x2000, v1
	v_ashrrev_i32_e32 v4, 31, v2
	v_lshrrev_b32_e32 v4, 22, v4
	v_add_u32_e32 v4, v2, v4
	v_ashrrev_i32_e32 v13, 10, v4
	v_mul_i32_i24_e32 v4, 0x400, v13
	v_sub_u32_e32 v2, v2, v4
	v_lshrrev_b32_e32 v4, 4, v2
	v_bitop3_b32 v2, v4, v2, 32 bitop3:0x6c
	v_ashrrev_i32_e32 v4, 31, v2
	v_lshrrev_b32_e32 v4, 26, v4
	v_add_u32_e32 v4, v2, v4
	s_waitcnt vmcnt(0)
	v_ashrrev_i32_e32 v14, 6, v4
	v_lshlrev_b32_e32 v6, 5, v13
	v_and_b32_e32 v4, 0xc0, v4
	s_load_dwordx4 s[48:51], s[12:13], 0x90
	s_load_dwordx2 s[18:19], s[12:13], 0x70
	v_and_b32_e32 v15, 32, v6
	v_sub_u32_e32 v2, v2, v4
	v_mov_b32_e32 v6, 1
	v_ashrrev_i16_sdwa v2, v6, sext(v2) dst_sel:DWORD dst_unused:UNUSED_PAD src0_sel:DWORD src1_sel:BYTE_0
	v_bfe_i32 v16, v2, 0, 16
	v_bfe_i32 v2, v12, 27, 1
	v_lshrrev_b32_e32 v2, 22, v2
	v_add_u32_e32 v2, v1, v2
	s_waitcnt lgkmcnt(0)
	s_add_u32 s26, s50, 0x20000000
	v_and_b32_e32 v2, 0xfffffc00, v2
	s_addc_u32 s27, s51, 0
	v_sub_u32_e32 v1, v1, v2
	s_add_u32 s30, s50, 0x5e00000
	v_readlane_b32 s14, v254, 62
	v_lshrrev_b32_e32 v2, 4, v1
	s_addc_u32 s31, s51, 0
	v_readlane_b32 s15, v254, 63
	v_bitop3_b32 v1, v2, v1, 32 bitop3:0x6c
	v_ashrrev_i32_e32 v4, 31, v12
	s_and_b64 s[14:15], s[14:15], exec
	v_lshlrev_b32_e32 v5, 3, v13
	v_ashrrev_i32_e32 v2, 31, v1
	v_lshrrev_b32_e32 v4, 26, v4
	s_cselect_b32 s1, 0, 0x90
	v_and_b32_e32 v5, 0x7fff0, v5
	v_lshrrev_b32_e32 v2, 26, v2
	v_add_u32_e32 v4, v12, v4
	s_add_u32 s12, s12, s1
	v_add_u32_e32 v5, v14, v5
	v_add_u32_e32 v2, v1, v2
	v_ashrrev_i32_e32 v18, 6, v4
	s_addc_u32 s13, s13, 0
	s_ashr_i32 s3, s0, 6
	v_lshl_or_b32 v5, v5, 12, v15
	v_ashrrev_i32_e32 v17, 6, v2
	v_lshlrev_b32_e32 v4, 3, v18
	v_and_b32_e32 v2, 0xc0, v2
	s_ashr_i32 s1, s0, 8
	s_cbranch_scc1 .Lsp_p5
	s_setprio 1

.LBB0_1148:
	s_cmp_le_i32 s28, s0
	s_cselect_b64 s[0:1], -1, 0
	v_readlane_b32 s3, v255, 2
	s_and_b64 s[0:1], s[0:1], s[6:7]
	s_add_i32 s34, s3, 8
	s_cmp_lt_i32 s34, s29
	s_cselect_b64 s[6:7], -1, 0
	s_andn2_b64 vcc, exec, s[0:1]
	s_cbranch_vccnz .LBB0_1219
	v_readlane_b32 s0, v253, 6
	v_mov_b32_e32 v1, v0
	s_mov_b64 s[12:13], s[72:73]
	s_waitcnt vmcnt(1)
	v_mov_b32_e32 v12, v0
	v_readlane_b32 s1, v253, 7
	s_andn2_b64 vcc, exec, s[0:1]
	v_readfirstlane_b32 s0, v12
	s_cbranch_vccnz .LBB0_1165
	v_lshlrev_b32_e32 v1, 4, v12
	v_add_u32_e32 v2, 0x2000, v1
	v_ashrrev_i32_e32 v4, 31, v2
	v_lshrrev_b32_e32 v4, 22, v4
	v_add_u32_e32 v4, v2, v4
	v_ashrrev_i32_e32 v13, 10, v4
	v_mul_i32_i24_e32 v4, 0x400, v13
	v_sub_u32_e32 v2, v2, v4
	v_lshrrev_b32_e32 v4, 4, v2
	v_bitop3_b32 v2, v4, v2, 32 bitop3:0x6c
	v_ashrrev_i32_e32 v4, 31, v2
	v_lshrrev_b32_e32 v4, 26, v4
	v_add_u32_e32 v4, v2, v4
	s_waitcnt lgkmcnt(0)
	v_lshlrev_b32_e32 v5, 3, v13
	s_waitcnt vmcnt(0)
	v_ashrrev_i32_e32 v14, 6, v4
	v_and_b32_e32 v5, -16, v5
	v_add_u32_e32 v5, v14, v5
	s_load_dwordx2 s[22:23], s[12:13], 0x98
	v_and_b32_e32 v6, 3, v14
	s_mov_b32 s12, 0x7ffe0
	v_lshrrev_b32_e32 v7, 2, v5
	v_lshlrev_b32_e32 v8, 1, v5
	v_and_or_b32 v6, v5, s12, v6
	v_and_b32_e32 v7, 4, v7
	v_and_b32_e32 v8, 24, v8
	v_and_b32_e32 v4, 0xc0, v4
	v_or3_b32 v6, v6, v7, v8
	v_sub_u32_e32 v2, v2, v4
	v_mov_b32_e32 v8, 1
	v_lshlrev_b32_e32 v7, 5, v13
	v_ashrrev_i16_sdwa v2, v8, sext(v2) dst_sel:DWORD dst_unused:UNUSED_PAD src0_sel:DWORD src1_sel:BYTE_0
	v_and_b32_e32 v7, 32, v7
	v_bfe_i32 v15, v2, 0, 16
	v_add_lshl_u32 v2, v7, v15, 1
	v_lshl_add_u32 v132, v6, 13, v2
	v_lshl_add_u32 v134, v5, 13, v2
	v_bfe_i32 v2, v12, 27, 1
	v_lshrrev_b32_e32 v2, 22, v2
	v_add_u32_e32 v2, v1, v2
	v_and_b32_e32 v2, 0xfffffc00, v2
	v_sub_u32_e32 v1, v1, v2
	v_lshrrev_b32_e32 v2, 4, v1
	v_ashrrev_i32_e32 v4, 31, v12
	v_bitop3_b32 v1, v2, v1, 32 bitop3:0x6c
	v_lshrrev_b32_e32 v4, 26, v4
	v_ashrrev_i32_e32 v2, 31, v1
	v_add_u32_e32 v4, v12, v4
	v_lshrrev_b32_e32 v2, 26, v2
	v_ashrrev_i32_e32 v17, 6, v4
	v_add_u32_e32 v2, v1, v2
	v_lshlrev_b32_e32 v4, 3, v17
	s_waitcnt lgkmcnt(0)
	s_add_u32 s26, s22, 0x18000000
	v_ashrrev_i32_e32 v16, 6, v2
	v_and_b32_e32 v4, -16, v4
	s_addc_u32 s27, s23, 0
	v_add_u32_e32 v4, v16, v4
	s_add_u32 s30, s22, 0x7e00000
	v_and_b32_e32 v5, 3, v16
	v_lshrrev_b32_e32 v6, 2, v4
	v_lshlrev_b32_e32 v7, 1, v4
	v_and_b32_e32 v2, 0xc0, v2
	s_addc_u32 s31, s23, 0
	s_ashr_i32 s3, s0, 6
	v_and_or_b32 v5, v4, s12, v5
	v_and_b32_e32 v6, 4, v6
	v_and_b32_e32 v7, 24, v7
	v_sub_u32_e32 v1, v1, v2
	s_ashr_i32 s1, s0, 8
	s_cbranch_scc1 .Lsp_p7
	s_setprio 1

.LBB0_1220:
	s_mov_b64 s[96:97], 0x8000
	v_mov_b32_e32 v1, v0
	s_mov_b64 s[6:7], s[72:73]
	s_waitcnt vmcnt(1)
	v_mov_b32_e32 v12, v0
	s_and_b64 vcc, exec, s[38:39]
	v_readfirstlane_b32 s18, v12
	s_cbranch_vccnz .LBB0_1294
	v_lshlrev_b32_e32 v1, 4, v12
	v_add_u32_e32 v2, 0x2000, v1
	v_ashrrev_i32_e32 v4, 31, v2
	v_lshrrev_b32_e32 v4, 22, v4
	v_add_u32_e32 v4, v2, v4
	v_ashrrev_i32_e32 v13, 10, v4
	v_mul_i32_i24_e32 v4, 0x400, v13
	v_sub_u32_e32 v2, v2, v4
	v_lshrrev_b32_e32 v4, 4, v2
	v_bitop3_b32 v2, v4, v2, 32 bitop3:0x6c
	v_ashrrev_i32_e32 v4, 31, v2
	v_lshrrev_b32_e32 v4, 26, v4
	v_add_u32_e32 v4, v2, v4
	s_waitcnt vmcnt(0)
	v_ashrrev_i32_e32 v14, 6, v4
	v_lshlrev_b32_e32 v6, 5, v13
	v_and_b32_e32 v4, 0xc0, v4
	v_and_b32_e32 v15, 32, v6
	v_sub_u32_e32 v2, v2, v4
	v_mov_b32_e32 v6, 1
	v_ashrrev_i16_sdwa v2, v6, sext(v2) dst_sel:DWORD dst_unused:UNUSED_PAD src0_sel:DWORD src1_sel:BYTE_0
	v_bfe_i32 v16, v2, 0, 16
	v_bfe_i32 v2, v12, 27, 1
	v_lshrrev_b32_e32 v2, 22, v2
	v_add_u32_e32 v2, v1, v2
	v_and_b32_e32 v2, 0xfffffc00, v2
	s_load_dwordx4 s[48:51], s[6:7], 0x90
	s_load_dwordx2 s[16:17], s[6:7], 0x8
	v_sub_u32_e32 v1, v1, v2
	v_lshrrev_b32_e32 v2, 4, v1
	v_ashrrev_i32_e32 v4, 31, v12
	v_bitop3_b32 v1, v2, v1, 32 bitop3:0x6c
	v_lshrrev_b32_e32 v4, 26, v4
	s_waitcnt lgkmcnt(0)
	v_lshlrev_b32_e32 v5, 3, v13
	v_ashrrev_i32_e32 v2, 31, v1
	v_add_u32_e32 v4, v12, v4
	s_add_u32 s0, s50, 0x28000000
	v_and_b32_e32 v5, 0xfffff0, v5
	v_lshrrev_b32_e32 v2, 26, v2
	v_ashrrev_i32_e32 v18, 6, v4
	s_addc_u32 s1, s51, 0
	v_add_u32_e32 v5, v14, v5
	s_movk_i32 s6, 0x40
	v_add_u32_e32 v2, v1, v2
	v_lshlrev_b32_e32 v4, 3, v18
	s_add_u32 s3, s50, 0x12a00000
	v_mul_lo_u32 v5, v5, s6
	v_ashrrev_i32_e32 v17, 6, v2
	v_and_b32_e32 v4, 0xfffff0, v4
	s_addc_u32 s26, s51, 0
	s_ashr_i32 s24, s18, 6
	v_or_b32_e32 v5, v5, v15
	v_add_u32_e32 v4, v17, v4
	v_and_b32_e32 v2, 0xc0, v2
	v_readlane_b32 s7, v253, 17
	s_ashr_i32 s19, s18, 8
	s_cbranch_scc1 .Lsp_p8
	s_setprio 1
